# v21 + phase-end drain removal + relaxed first two waits of a projection unit that follows an epilogue (its stores need not retire first)
# speedup vs baseline: 1.0080x; 1.0080x over previous
.LBB0_105:
	v_mov_b32_e32 v165, v27
	v_lshl_add_u64 v[58:59], s[86:87], 0, v[164:165]
	v_mov_b32_e32 v161, v27
	v_lshl_add_u64 v[84:85], s[86:87], 0, v[160:161]
	s_add_i32 m0, s17, 0x18000
	v_lshl_add_u64 v[58:59], v[58:59], 0, s[82:83]
	v_readlane_b32 s26, v251, 55
	v_mov_b32_e32 v167, v27
	global_load_lds_dwordx4 v[58:59], off
	v_lshl_add_u64 v[58:59], v[84:85], 0, s[82:83]
	s_add_i32 m0, s17, 0x1a000
	v_readlane_b32 s27, v251, 56
	s_add_i32 s22, s17, 0x8000
	v_mov_b32_e32 v163, v27
	global_load_lds_dwordx4 v[58:59], off
	v_lshl_add_u64 v[58:59], s[26:27], 0, v[166:167]
	s_mov_b32 m0, s22
	s_add_i32 s80, s17, 0xa000
	global_load_lds_dwordx4 v[58:59], off
	v_lshl_add_u64 v[58:59], s[26:27], 0, v[162:163]
	s_mov_b32 m0, s80
	s_and_b32 s1, s1, 3
	global_load_lds_dwordx4 v[58:59], off
	s_add_i32 m0, s17, 0x1c000
	v_lshl_add_u64 v[58:59], s[52:53], 0, v[164:165]
	global_load_lds_dwordx4 v[58:59], off
	v_lshl_add_u64 v[58:59], s[52:53], 0, v[160:161]
	s_add_i32 m0, s17, 0x1e000
	v_mul_lo_u32 v26, v26, s7
	global_load_lds_dwordx4 v[58:59], off
	s_waitcnt vmcnt(8)
	s_barrier
	v_bfe_u32 v59, v37, 4, 2
	v_and_b32_e32 v58, 15, v37
	v_lshlrev_b32_e32 v185, 4, v59
	v_lshlrev_b32_e32 v37, 2, v37
	v_lshl_or_b32 v184, s11, 6, v58
	v_lshl_or_b32 v58, v58, 6, v185
	s_lshl_b32 s11, s11, 13
	v_and_b32_e32 v37, 32, v37
	v_bitop3_b32 v84, v58, s11, v37 bitop3:0xde
	s_lshl_b32 s11, s1, 12
	v_bitop3_b32 v186, v58, s11, v37 bitop3:0xde
	s_cmpk_lt_u32 s0, 0x100
	v_lshrrev_b32_e32 v37, 1, v56
	v_mul_lo_u32 v58, v39, s7
	s_mov_b32 s11, 0x2c000
	s_cselect_b64 s[60:61], -1, 0
	v_cmp_eq_u32_e64 s[38:39], 0, v59
	s_lshl_b32 s26, s1, 1
	v_lshl_or_b32 v187, s1, 6, v185
	v_mad_u64_u32 v[58:59], s[0:1], v37, s11, v[58:59]
	v_and_b32_e32 v37, 1, v56
	v_lshl_or_b32 v37, v37, 6, v58
	v_lshl_add_u32 v176, v57, 1, v37
	v_lshrrev_b32_e32 v37, 1, v36
	v_mad_u64_u32 v[56:57], s[0:1], v37, s11, v[26:27]
	s_waitcnt vmcnt(6)
	v_and_b32_e32 v26, 1, v36
	v_readlane_b32 s0, v251, 36
	v_lshl_or_b32 v26, v26, 6, v56
	s_mov_b32 s94, s0
	v_readlane_b32 s0, v251, 34
	v_readlane_b32 s78, v251, 37
	s_mov_b32 s81, 0
	s_orn2_b32 s26, s26, 47
	v_mov_b32_e32 v177, v27
	v_lshl_add_u32 v178, v38, 1, v26
	v_mov_b32_e32 v179, v27
	v_add_u32_e32 v188, 0, v84
	v_readlane_b32 s31, v251, 35
	s_mov_b32 s30, s0
	s_mov_b64 s[76:77], s[86:87]
	v_readlane_b32 s79, v251, 38
	s_barrier
	s_mov_b32 s98, 0
	s_branch .LBB0_108
